# memory k/v projection distributed over all 256 workgroups (64x64 piece each, operands straight from global, same MFMA sequence per element) instead of 16 full tiles on workgroups 0-15
# speedup vs baseline: 1.1123x; 1.0007x over previous
.LBB0_452:
	v_readfirstlane_b32 s0, v168
	s_lshr_b32 s0, s0, 6
	s_cmp_gt_u32 s0, 3
	s_cbranch_scc1 .LBB0_463
	s_lshr_b32 s1, s2, 7
	s_bfe_u32 s4, s2, 0x30004
	s_and_b32 s5, s2, 15
	s_and_b32 s6, s0, 1
	s_bfe_u32 s7, s0, 0x10001
	s_lshl_b32 s4, s4, 1
	s_or_b32 s4, s4, s6
	s_lshl_b32 s5, s5, 1
	s_or_b32 s5, s5, s7
	s_lshl_b32 s6, s1, 20
	s_lshl_b32 s7, s4, 16
	s_add_u32 s10, s6, s7
	s_add_u32 s8, s10, 0xde00000
	s_add_u32 s8, s86, s8
	s_addc_u32 s9, s87, 0
	s_lshl_b32 s6, s1, 21
	s_lshl_b32 s7, s5, 16
	s_add_u32 s6, s6, s7
	s_add_u32 s6, s6, 0xda00000
	s_add_u32 s12, s86, s6
	s_addc_u32 s13, s87, 0
	s_lshl_b32 s7, s5, 6
	s_add_u32 s10, s10, s7
	s_add_u32 s10, s10, 0xe000000
	s_add_u32 s10, s86, s10
	s_addc_u32 s11, s87, 0
	v_and_b32_e32 v147, 31, v168
	v_bfe_u32 v146, v168, 5, 1
	v_lshlrev_b32_e32 v144, 11, v147
	v_lshl_or_b32 v144, v146, 4, v144
	v_lshlrev_b32_e32 v145, 1, v147
	v_lshl_or_b32 v145, v146, 13, v145
	v_add_u32_e32 v146, 0x1000, v145
	global_load_dwordx4 v[16:19], v144, s[8:9]
	global_load_dwordx4 v[80:83], v144, s[12:13]
	global_load_dwordx4 v[20:23], v144, s[8:9] offset:32
	global_load_dwordx4 v[84:87], v144, s[12:13] offset:32
	global_load_dwordx4 v[24:27], v144, s[8:9] offset:64
	global_load_dwordx4 v[88:91], v144, s[12:13] offset:64
	global_load_dwordx4 v[28:31], v144, s[8:9] offset:96
	global_load_dwordx4 v[92:95], v144, s[12:13] offset:96
	global_load_dwordx4 v[32:35], v144, s[8:9] offset:128
	global_load_dwordx4 v[96:99], v144, s[12:13] offset:128
	global_load_dwordx4 v[36:39], v144, s[8:9] offset:160
	global_load_dwordx4 v[100:103], v144, s[12:13] offset:160
	global_load_dwordx4 v[40:43], v144, s[8:9] offset:192
	global_load_dwordx4 v[104:107], v144, s[12:13] offset:192
	global_load_dwordx4 v[44:47], v144, s[8:9] offset:224
	global_load_dwordx4 v[108:111], v144, s[12:13] offset:224
	global_load_dwordx4 v[48:51], v144, s[8:9] offset:256
	global_load_dwordx4 v[112:115], v144, s[12:13] offset:256
	global_load_dwordx4 v[52:55], v144, s[8:9] offset:288
	global_load_dwordx4 v[116:119], v144, s[12:13] offset:288
	global_load_dwordx4 v[56:59], v144, s[8:9] offset:320
	global_load_dwordx4 v[120:123], v144, s[12:13] offset:320
	global_load_dwordx4 v[60:63], v144, s[8:9] offset:352
	global_load_dwordx4 v[124:127], v144, s[12:13] offset:352
	global_load_dwordx4 v[64:67], v144, s[8:9] offset:384
	global_load_dwordx4 v[128:131], v144, s[12:13] offset:384
	global_load_dwordx4 v[68:71], v144, s[8:9] offset:416
	global_load_dwordx4 v[132:135], v144, s[12:13] offset:416
	global_load_dwordx4 v[72:75], v144, s[8:9] offset:448
	global_load_dwordx4 v[136:139], v144, s[12:13] offset:448
	global_load_dwordx4 v[76:79], v144, s[8:9] offset:480
	global_load_dwordx4 v[140:143], v144, s[12:13] offset:480
	s_waitcnt vmcnt(30)
	v_mfma_f32_32x32x16_bf16 v[0:15], v[16:19], v[80:83], 0
	global_load_dwordx4 v[16:19], v144, s[8:9] offset:512
	global_load_dwordx4 v[80:83], v144, s[12:13] offset:512
	s_waitcnt vmcnt(30)
	v_mfma_f32_32x32x16_bf16 v[0:15], v[20:23], v[84:87], v[0:15]
	global_load_dwordx4 v[20:23], v144, s[8:9] offset:544
	global_load_dwordx4 v[84:87], v144, s[12:13] offset:544
	s_waitcnt vmcnt(30)
	v_mfma_f32_32x32x16_bf16 v[0:15], v[24:27], v[88:91], v[0:15]
	global_load_dwordx4 v[24:27], v144, s[8:9] offset:576
	global_load_dwordx4 v[88:91], v144, s[12:13] offset:576
	s_waitcnt vmcnt(30)
	v_mfma_f32_32x32x16_bf16 v[0:15], v[28:31], v[92:95], v[0:15]
	global_load_dwordx4 v[28:31], v144, s[8:9] offset:608
	global_load_dwordx4 v[92:95], v144, s[12:13] offset:608
	s_waitcnt vmcnt(30)
	v_mfma_f32_32x32x16_bf16 v[0:15], v[32:35], v[96:99], v[0:15]
	global_load_dwordx4 v[32:35], v144, s[8:9] offset:640
	global_load_dwordx4 v[96:99], v144, s[12:13] offset:640
	s_waitcnt vmcnt(30)
	v_mfma_f32_32x32x16_bf16 v[0:15], v[36:39], v[100:103], v[0:15]
	global_load_dwordx4 v[36:39], v144, s[8:9] offset:672
	global_load_dwordx4 v[100:103], v144, s[12:13] offset:672
	s_waitcnt vmcnt(30)
	v_mfma_f32_32x32x16_bf16 v[0:15], v[40:43], v[104:107], v[0:15]
	global_load_dwordx4 v[40:43], v144, s[8:9] offset:704
	global_load_dwordx4 v[104:107], v144, s[12:13] offset:704
	s_waitcnt vmcnt(30)
	v_mfma_f32_32x32x16_bf16 v[0:15], v[44:47], v[108:111], v[0:15]
	global_load_dwordx4 v[44:47], v144, s[8:9] offset:736
	global_load_dwordx4 v[108:111], v144, s[12:13] offset:736
	s_waitcnt vmcnt(30)
	v_mfma_f32_32x32x16_bf16 v[0:15], v[48:51], v[112:115], v[0:15]
	global_load_dwordx4 v[48:51], v144, s[8:9] offset:768
	global_load_dwordx4 v[112:115], v144, s[12:13] offset:768
	s_waitcnt vmcnt(30)
	v_mfma_f32_32x32x16_bf16 v[0:15], v[52:55], v[116:119], v[0:15]
	global_load_dwordx4 v[52:55], v144, s[8:9] offset:800
	global_load_dwordx4 v[116:119], v144, s[12:13] offset:800
	s_waitcnt vmcnt(30)
	v_mfma_f32_32x32x16_bf16 v[0:15], v[56:59], v[120:123], v[0:15]
	global_load_dwordx4 v[56:59], v144, s[8:9] offset:832
	global_load_dwordx4 v[120:123], v144, s[12:13] offset:832
	s_waitcnt vmcnt(30)
	v_mfma_f32_32x32x16_bf16 v[0:15], v[60:63], v[124:127], v[0:15]
	global_load_dwordx4 v[60:63], v144, s[8:9] offset:864
	global_load_dwordx4 v[124:127], v144, s[12:13] offset:864
	s_waitcnt vmcnt(30)
	v_mfma_f32_32x32x16_bf16 v[0:15], v[64:67], v[128:131], v[0:15]
	global_load_dwordx4 v[64:67], v144, s[8:9] offset:896
	global_load_dwordx4 v[128:131], v144, s[12:13] offset:896
	s_waitcnt vmcnt(30)
	v_mfma_f32_32x32x16_bf16 v[0:15], v[68:71], v[132:135], v[0:15]
	global_load_dwordx4 v[68:71], v144, s[8:9] offset:928
	global_load_dwordx4 v[132:135], v144, s[12:13] offset:928
	s_waitcnt vmcnt(30)
	v_mfma_f32_32x32x16_bf16 v[0:15], v[72:75], v[136:139], v[0:15]
	global_load_dwordx4 v[72:75], v144, s[8:9] offset:960
	global_load_dwordx4 v[136:139], v144, s[12:13] offset:960
	s_waitcnt vmcnt(30)
	v_mfma_f32_32x32x16_bf16 v[0:15], v[76:79], v[140:143], v[0:15]
	global_load_dwordx4 v[76:79], v144, s[8:9] offset:992
	global_load_dwordx4 v[140:143], v144, s[12:13] offset:992
	s_waitcnt vmcnt(30)
	v_mfma_f32_32x32x16_bf16 v[0:15], v[16:19], v[80:83], v[0:15]
	global_load_dwordx4 v[16:19], v144, s[8:9] offset:1024
	global_load_dwordx4 v[80:83], v144, s[12:13] offset:1024
	s_waitcnt vmcnt(30)
	v_mfma_f32_32x32x16_bf16 v[0:15], v[20:23], v[84:87], v[0:15]
	global_load_dwordx4 v[20:23], v144, s[8:9] offset:1056
	global_load_dwordx4 v[84:87], v144, s[12:13] offset:1056
	s_waitcnt vmcnt(30)
	v_mfma_f32_32x32x16_bf16 v[0:15], v[24:27], v[88:91], v[0:15]
	global_load_dwordx4 v[24:27], v144, s[8:9] offset:1088
	global_load_dwordx4 v[88:91], v144, s[12:13] offset:1088
	s_waitcnt vmcnt(30)
	v_mfma_f32_32x32x16_bf16 v[0:15], v[28:31], v[92:95], v[0:15]
	global_load_dwordx4 v[28:31], v144, s[8:9] offset:1120
	global_load_dwordx4 v[92:95], v144, s[12:13] offset:1120
	s_waitcnt vmcnt(30)
	v_mfma_f32_32x32x16_bf16 v[0:15], v[32:35], v[96:99], v[0:15]
	global_load_dwordx4 v[32:35], v144, s[8:9] offset:1152
	global_load_dwordx4 v[96:99], v144, s[12:13] offset:1152
	s_waitcnt vmcnt(30)
	v_mfma_f32_32x32x16_bf16 v[0:15], v[36:39], v[100:103], v[0:15]
	global_load_dwordx4 v[36:39], v144, s[8:9] offset:1184
	global_load_dwordx4 v[100:103], v144, s[12:13] offset:1184
	s_waitcnt vmcnt(30)
	v_mfma_f32_32x32x16_bf16 v[0:15], v[40:43], v[104:107], v[0:15]
	global_load_dwordx4 v[40:43], v144, s[8:9] offset:1216
	global_load_dwordx4 v[104:107], v144, s[12:13] offset:1216
	s_waitcnt vmcnt(30)
	v_mfma_f32_32x32x16_bf16 v[0:15], v[44:47], v[108:111], v[0:15]
	global_load_dwordx4 v[44:47], v144, s[8:9] offset:1248
	global_load_dwordx4 v[108:111], v144, s[12:13] offset:1248
	s_waitcnt vmcnt(30)
	v_mfma_f32_32x32x16_bf16 v[0:15], v[48:51], v[112:115], v[0:15]
	global_load_dwordx4 v[48:51], v144, s[8:9] offset:1280
	global_load_dwordx4 v[112:115], v144, s[12:13] offset:1280
	s_waitcnt vmcnt(30)
	v_mfma_f32_32x32x16_bf16 v[0:15], v[52:55], v[116:119], v[0:15]
	global_load_dwordx4 v[52:55], v144, s[8:9] offset:1312
	global_load_dwordx4 v[116:119], v144, s[12:13] offset:1312
	s_waitcnt vmcnt(30)
	v_mfma_f32_32x32x16_bf16 v[0:15], v[56:59], v[120:123], v[0:15]
	global_load_dwordx4 v[56:59], v144, s[8:9] offset:1344
	global_load_dwordx4 v[120:123], v144, s[12:13] offset:1344
	s_waitcnt vmcnt(30)
	v_mfma_f32_32x32x16_bf16 v[0:15], v[60:63], v[124:127], v[0:15]
	global_load_dwordx4 v[60:63], v144, s[8:9] offset:1376
	global_load_dwordx4 v[124:127], v144, s[12:13] offset:1376
	s_waitcnt vmcnt(30)
	v_mfma_f32_32x32x16_bf16 v[0:15], v[64:67], v[128:131], v[0:15]
	global_load_dwordx4 v[64:67], v144, s[8:9] offset:1408
	global_load_dwordx4 v[128:131], v144, s[12:13] offset:1408
	s_waitcnt vmcnt(30)
	v_mfma_f32_32x32x16_bf16 v[0:15], v[68:71], v[132:135], v[0:15]
	global_load_dwordx4 v[68:71], v144, s[8:9] offset:1440
	global_load_dwordx4 v[132:135], v144, s[12:13] offset:1440
	s_waitcnt vmcnt(30)
	v_mfma_f32_32x32x16_bf16 v[0:15], v[72:75], v[136:139], v[0:15]
	global_load_dwordx4 v[72:75], v144, s[8:9] offset:1472
	global_load_dwordx4 v[136:139], v144, s[12:13] offset:1472
	s_waitcnt vmcnt(30)
	v_mfma_f32_32x32x16_bf16 v[0:15], v[76:79], v[140:143], v[0:15]
	global_load_dwordx4 v[76:79], v144, s[8:9] offset:1504
	global_load_dwordx4 v[140:143], v144, s[12:13] offset:1504
	s_waitcnt vmcnt(30)
	v_mfma_f32_32x32x16_bf16 v[0:15], v[16:19], v[80:83], v[0:15]
	global_load_dwordx4 v[16:19], v144, s[8:9] offset:1536
	global_load_dwordx4 v[80:83], v144, s[12:13] offset:1536
	s_waitcnt vmcnt(30)
	v_mfma_f32_32x32x16_bf16 v[0:15], v[20:23], v[84:87], v[0:15]
	global_load_dwordx4 v[20:23], v144, s[8:9] offset:1568
	global_load_dwordx4 v[84:87], v144, s[12:13] offset:1568
	s_waitcnt vmcnt(30)
	v_mfma_f32_32x32x16_bf16 v[0:15], v[24:27], v[88:91], v[0:15]
	global_load_dwordx4 v[24:27], v144, s[8:9] offset:1600
	global_load_dwordx4 v[88:91], v144, s[12:13] offset:1600
	s_waitcnt vmcnt(30)
	v_mfma_f32_32x32x16_bf16 v[0:15], v[28:31], v[92:95], v[0:15]
	global_load_dwordx4 v[28:31], v144, s[8:9] offset:1632
	global_load_dwordx4 v[92:95], v144, s[12:13] offset:1632
	s_waitcnt vmcnt(30)
	v_mfma_f32_32x32x16_bf16 v[0:15], v[32:35], v[96:99], v[0:15]
	global_load_dwordx4 v[32:35], v144, s[8:9] offset:1664
	global_load_dwordx4 v[96:99], v144, s[12:13] offset:1664
	s_waitcnt vmcnt(30)
	v_mfma_f32_32x32x16_bf16 v[0:15], v[36:39], v[100:103], v[0:15]
	global_load_dwordx4 v[36:39], v144, s[8:9] offset:1696
	global_load_dwordx4 v[100:103], v144, s[12:13] offset:1696
	s_waitcnt vmcnt(30)
	v_mfma_f32_32x32x16_bf16 v[0:15], v[40:43], v[104:107], v[0:15]
	global_load_dwordx4 v[40:43], v144, s[8:9] offset:1728
	global_load_dwordx4 v[104:107], v144, s[12:13] offset:1728
	s_waitcnt vmcnt(30)
	v_mfma_f32_32x32x16_bf16 v[0:15], v[44:47], v[108:111], v[0:15]
	global_load_dwordx4 v[44:47], v144, s[8:9] offset:1760
	global_load_dwordx4 v[108:111], v144, s[12:13] offset:1760
	s_waitcnt vmcnt(30)
	v_mfma_f32_32x32x16_bf16 v[0:15], v[48:51], v[112:115], v[0:15]
	global_load_dwordx4 v[48:51], v144, s[8:9] offset:1792
	global_load_dwordx4 v[112:115], v144, s[12:13] offset:1792
	s_waitcnt vmcnt(30)
	v_mfma_f32_32x32x16_bf16 v[0:15], v[52:55], v[116:119], v[0:15]
	global_load_dwordx4 v[52:55], v144, s[8:9] offset:1824
	global_load_dwordx4 v[116:119], v144, s[12:13] offset:1824
	s_waitcnt vmcnt(30)
	v_mfma_f32_32x32x16_bf16 v[0:15], v[56:59], v[120:123], v[0:15]
	global_load_dwordx4 v[56:59], v144, s[8:9] offset:1856
	global_load_dwordx4 v[120:123], v144, s[12:13] offset:1856
	s_waitcnt vmcnt(30)
	v_mfma_f32_32x32x16_bf16 v[0:15], v[60:63], v[124:127], v[0:15]
	global_load_dwordx4 v[60:63], v144, s[8:9] offset:1888
	global_load_dwordx4 v[124:127], v144, s[12:13] offset:1888
	s_waitcnt vmcnt(30)
	v_mfma_f32_32x32x16_bf16 v[0:15], v[64:67], v[128:131], v[0:15]
	global_load_dwordx4 v[64:67], v144, s[8:9] offset:1920
	global_load_dwordx4 v[128:131], v144, s[12:13] offset:1920
	s_waitcnt vmcnt(30)
	v_mfma_f32_32x32x16_bf16 v[0:15], v[68:71], v[132:135], v[0:15]
	global_load_dwordx4 v[68:71], v144, s[8:9] offset:1952
	global_load_dwordx4 v[132:135], v144, s[12:13] offset:1952
	s_waitcnt vmcnt(30)
	v_mfma_f32_32x32x16_bf16 v[0:15], v[72:75], v[136:139], v[0:15]
	global_load_dwordx4 v[72:75], v144, s[8:9] offset:1984
	global_load_dwordx4 v[136:139], v144, s[12:13] offset:1984
	s_waitcnt vmcnt(30)
	v_mfma_f32_32x32x16_bf16 v[0:15], v[76:79], v[140:143], v[0:15]
	global_load_dwordx4 v[76:79], v144, s[8:9] offset:2016
	global_load_dwordx4 v[140:143], v144, s[12:13] offset:2016
	s_waitcnt vmcnt(30)
	v_mfma_f32_32x32x16_bf16 v[0:15], v[16:19], v[80:83], v[0:15]
	s_waitcnt vmcnt(28)
	v_mfma_f32_32x32x16_bf16 v[0:15], v[20:23], v[84:87], v[0:15]
	s_waitcnt vmcnt(26)
	v_mfma_f32_32x32x16_bf16 v[0:15], v[24:27], v[88:91], v[0:15]
	s_waitcnt vmcnt(24)
	v_mfma_f32_32x32x16_bf16 v[0:15], v[28:31], v[92:95], v[0:15]
	s_waitcnt vmcnt(22)
	v_mfma_f32_32x32x16_bf16 v[0:15], v[32:35], v[96:99], v[0:15]
	s_waitcnt vmcnt(20)
	v_mfma_f32_32x32x16_bf16 v[0:15], v[36:39], v[100:103], v[0:15]
	s_waitcnt vmcnt(18)
	v_mfma_f32_32x32x16_bf16 v[0:15], v[40:43], v[104:107], v[0:15]
	s_waitcnt vmcnt(16)
	v_mfma_f32_32x32x16_bf16 v[0:15], v[44:47], v[108:111], v[0:15]
	s_waitcnt vmcnt(14)
	v_mfma_f32_32x32x16_bf16 v[0:15], v[48:51], v[112:115], v[0:15]
	s_waitcnt vmcnt(12)
	v_mfma_f32_32x32x16_bf16 v[0:15], v[52:55], v[116:119], v[0:15]
	s_waitcnt vmcnt(10)
	v_mfma_f32_32x32x16_bf16 v[0:15], v[56:59], v[120:123], v[0:15]
	s_waitcnt vmcnt(8)
	v_mfma_f32_32x32x16_bf16 v[0:15], v[60:63], v[124:127], v[0:15]
	s_waitcnt vmcnt(6)
	v_mfma_f32_32x32x16_bf16 v[0:15], v[64:67], v[128:131], v[0:15]
	s_waitcnt vmcnt(4)
	v_mfma_f32_32x32x16_bf16 v[0:15], v[68:71], v[132:135], v[0:15]
	s_waitcnt vmcnt(2)
	v_mfma_f32_32x32x16_bf16 v[0:15], v[72:75], v[136:139], v[0:15]
	s_waitcnt vmcnt(0)
	v_mfma_f32_32x32x16_bf16 v[0:15], v[76:79], v[140:143], v[0:15]
	s_nop 7
	s_nop 7
	s_nop 7
	v_cvt_pk_bf16_f32 v147, v0, s0
	global_store_short v145, v147, s[10:11]
	v_cvt_pk_bf16_f32 v147, v1, s0
	global_store_short v145, v147, s[10:11] offset:2048
	v_cvt_pk_bf16_f32 v147, v2, s0
	global_store_short v146, v147, s[10:11]
	v_cvt_pk_bf16_f32 v147, v3, s0
	global_store_short v146, v147, s[10:11] offset:2048
	s_add_u32 s10, s10, 0x4000
	s_addc_u32 s11, s11, 0
	v_cvt_pk_bf16_f32 v147, v4, s0
	global_store_short v145, v147, s[10:11]
	v_cvt_pk_bf16_f32 v147, v5, s0
	global_store_short v145, v147, s[10:11] offset:2048
	v_cvt_pk_bf16_f32 v147, v6, s0
	global_store_short v146, v147, s[10:11]
	v_cvt_pk_bf16_f32 v147, v7, s0
	global_store_short v146, v147, s[10:11] offset:2048
	s_add_u32 s10, s10, 0x4000
	s_addc_u32 s11, s11, 0
	v_cvt_pk_bf16_f32 v147, v8, s0
	global_store_short v145, v147, s[10:11]
	v_cvt_pk_bf16_f32 v147, v9, s0
	global_store_short v145, v147, s[10:11] offset:2048
	v_cvt_pk_bf16_f32 v147, v10, s0
	global_store_short v146, v147, s[10:11]
	v_cvt_pk_bf16_f32 v147, v11, s0
	global_store_short v146, v147, s[10:11] offset:2048
	s_add_u32 s10, s10, 0x4000
	s_addc_u32 s11, s11, 0
	v_cvt_pk_bf16_f32 v147, v12, s0
	global_store_short v145, v147, s[10:11]
	v_cvt_pk_bf16_f32 v147, v13, s0
	global_store_short v145, v147, s[10:11] offset:2048
	v_cvt_pk_bf16_f32 v147, v14, s0
	global_store_short v146, v147, s[10:11]
	v_cvt_pk_bf16_f32 v147, v15, s0
	global_store_short v146, v147, s[10:11] offset:2048
